# v16: v12 + ret_scan MFMA section: tr-read pairs pipelined through a ring of 4 quads (2 runs)
# speedup vs baseline: 1.0042x; 1.0042x over previous
; #define LAS __attribute__((address_space(3)))
; __device__ __forceinline__ s16x4 tr16(const LAS unsigned char* p) { return __builtin_bit_cast(s16x4, __builtin_amdgcn_ds_read_tr16_b64_v4i16((LAS s16x4*)p)); }
; __device__ __forceinline__ bf16x8 cat8(s16x4 lo, s16x4 hi) { return __builtin_shufflevector(lo, hi, 0, 1, 2, 3, 4, 5, 6, 7); }
; __device__ __forceinline__ f32x4 mfma16(bf16x8 a, bf16x8 b, f32x4 c) { return __builtin_amdgcn_mfma_f32_16x16x32_bf16(a, b, c, 0, 0, 0); }
; __device__ __forceinline__ void ret_scan(const bf16* proj, bf16* ST, bf16* FS, const float* dexp, LAS unsigned char* lds, int vb, int nb, int tid_in, int wave) {
;     ...
;             for (int m = 0; m < 8; ++m) { acc[m][0] = acc[m][0] * gC; acc[m][1] = acc[m][1] * gC; }
; #pragma unroll
;             for (int ks = 0; ks < 4; ++ks) {
;                 const int rho = 8 * ks + 2 * g, lo8 = (qi >> 2) * 32 + (qi & 3) * 8;
;                 bf16x8 bfr[2];
; #pragma unroll
;                 for (int nt = 0; nt < 2; ++nt) { const LAS unsigned char* p = Vt + rho * 2112 + (2 * wave + nt) * 128 + lo8; bfr[nt] = cat8(tr16(p), tr16(p + 2112)); }
; #pragma unroll
;                 for (int m = 0; m < 8; ++m) { const LAS unsigned char* p = Kt + rho * 1088 + m * 128 + lo8; const bf16x8 af = cat8(tr16(p), tr16(p + 1088));
;                     acc[m][0] = mfma16(af, bfr[0], acc[m][0]); acc[m][1] = mfma16(af, bfr[1], acc[m][1]); }
;             }
.LBB0_414:
	v_mov_b32_e32 v149, v148
	v_pk_mul_f32 v[140:141], v[148:149], v[52:53]
	v_pk_mul_f32 v[138:139], v[158:159], v[50:51]
	v_pk_mul_f32 v[132:133], v[148:149], v[60:61]
	v_pk_mul_f32 v[130:131], v[158:159], v[58:59]
	v_pk_mul_f32 v[136:137], v[148:149], v[64:65]
	v_pk_mul_f32 v[134:135], v[158:159], v[62:63]
	v_pk_mul_f32 v[128:129], v[148:149], v[72:73]
	v_pk_mul_f32 v[126:127], v[158:159], v[70:71]
	v_pk_mul_f32 v[120:121], v[148:149], v[80:81]
	v_pk_mul_f32 v[118:119], v[158:159], v[78:79]
	v_pk_mul_f32 v[80:81], v[148:149], v[96:97]
	v_pk_mul_f32 v[78:79], v[158:159], v[94:95]
	v_pk_mul_f32 v[72:73], v[148:149], v[104:105]
	v_pk_mul_f32 v[70:71], v[158:159], v[102:103]
	v_pk_mul_f32 v[52:53], v[148:149], v[112:113]
	v_pk_mul_f32 v[50:51], v[158:159], v[110:111]
	ds_read_b64_tr_b16 v[62:63], v206 offset:34816
	ds_read_b64_tr_b16 v[64:65], v206 offset:36928
	ds_read_b64_tr_b16 v[58:59], v206 offset:34944
	ds_read_b64_tr_b16 v[60:61], v206 offset:37056
	ds_read_b64_tr_b16 v[94:95], v207
	ds_read_b64_tr_b16 v[96:97], v207 offset:1088
	ds_read_b64_tr_b16 v[102:103], v207 offset:128
	ds_read_b64_tr_b16 v[104:105], v207 offset:1216
	ds_read_b64_tr_b16 v[110:111], v207 offset:256
	ds_read_b64_tr_b16 v[112:113], v207 offset:1344
	v_pk_mul_f32 v[124:125], v[148:149], v[68:69]
	v_pk_mul_f32 v[122:123], v[158:159], v[66:67]
	v_pk_mul_f32 v[144:145], v[148:149], v[56:57]
	v_pk_mul_f32 v[142:143], v[158:159], v[54:55]
	v_pk_mul_f32 v[56:57], v[148:149], v[108:109]
	v_pk_mul_f32 v[54:55], v[158:159], v[106:107]
	s_waitcnt lgkmcnt(0)
	v_mfma_f32_16x16x32_bf16 v[106:109], v[110:113], v[62:65], v[122:125]
	s_nop 2
	ds_read_b64_tr_b16 v[122:123], v207 offset:384
	ds_read_b64_tr_b16 v[124:125], v207 offset:1472
	v_pk_mul_f32 v[116:117], v[148:149], v[76:77]
	v_pk_mul_f32 v[114:115], v[158:159], v[74:75]
	s_waitcnt lgkmcnt(0)
	v_mfma_f32_16x16x32_bf16 v[118:121], v[122:125], v[58:61], v[118:121]
	v_mul_f32_e64 v84, v148, v84
	v_mul_f32_e64 v85, v149, v85
	v_pk_mul_f32 v[82:83], v[158:159], v[82:83]
	v_pk_mul_f32 v[88:89], v[148:149], v[88:89]
	v_mfma_f32_16x16x32_bf16 v[114:117], v[122:125], v[62:65], v[114:117]
	ds_read_b64_tr_b16 v[122:123], v207 offset:512
	ds_read_b64_tr_b16 v[124:125], v207 offset:1600
	v_pk_mul_f32 v[86:87], v[158:159], v[86:87]
	v_pk_mul_f32 v[76:77], v[148:149], v[92:93]
	s_waitcnt lgkmcnt(0)
	v_mfma_f32_16x16x32_bf16 v[82:85], v[122:125], v[62:65], v[82:85]
	v_mul_f32_e64 v74, v158, v90
	v_mul_f32_e64 v75, v159, v91
	v_pk_mul_f32 v[68:69], v[148:149], v[100:101]
	v_pk_mul_f32 v[66:67], v[158:159], v[98:99]
	v_mfma_f32_16x16x32_bf16 v[86:89], v[122:125], v[58:61], v[86:89]
	ds_read_b64_tr_b16 v[122:123], v207 offset:640
	ds_read_b64_tr_b16 v[124:125], v207 offset:1728
	s_sub_i32 s37, 15, s59
	s_and_b64 s[30:31], s[4:5], exec
	s_waitcnt lgkmcnt(0)
	v_mfma_f32_16x16x32_bf16 v[74:77], v[122:125], v[62:65], v[74:77]
	s_cselect_b32 s37, s59, s37
	s_add_i32 s37, s37, s56
	s_lshl_b32 s30, s37, 3
	v_mfma_f32_16x16x32_bf16 v[78:81], v[122:125], v[58:61], v[78:81]
	ds_read_b64_tr_b16 v[122:123], v207 offset:768
	ds_read_b64_tr_b16 v[124:125], v207 offset:1856
	s_or_b32 s30, s30, s47
	s_ashr_i32 s31, s30, 31
	s_waitcnt lgkmcnt(0)
	v_mfma_f32_16x16x32_bf16 v[66:69], v[122:125], v[62:65], v[66:69]
	s_lshl_b64 s[30:31], s[30:31], 18
	s_add_u32 s30, s57, s30
	s_addc_u32 s31, s58, s31
	v_mfma_f32_16x16x32_bf16 v[70:73], v[122:125], v[58:61], v[70:73]
	ds_read_b64_tr_b16 v[122:123], v207 offset:896
	ds_read_b64_tr_b16 v[124:125], v207 offset:1984
	s_cmp_lt_u32 s59, 15
	s_cselect_b32 s51, s31, s55
	v_mfma_f32_16x16x32_bf16 v[90:93], v[94:97], v[62:65], v[138:141]
	s_cselect_b32 s50, s30, s54
	v_mfma_f32_16x16x32_bf16 v[94:97], v[94:97], v[58:61], v[142:145]
	v_mfma_f32_16x16x32_bf16 v[98:101], v[102:105], v[62:65], v[130:133]
	v_mfma_f32_16x16x32_bf16 v[102:105], v[102:105], v[58:61], v[134:137]
	v_mfma_f32_16x16x32_bf16 v[110:113], v[110:113], v[58:61], v[126:129]
	s_waitcnt lgkmcnt(0)
	v_mfma_f32_16x16x32_bf16 v[54:57], v[122:125], v[62:65], v[54:57]
	v_mfma_f32_16x16x32_bf16 v[50:53], v[122:125], v[58:61], v[50:53]
	ds_read_b64_tr_b16 v[58:59], v208 offset:34816
	ds_read_b64_tr_b16 v[60:61], v208 offset:36928
	ds_read_b64_tr_b16 v[62:63], v208 offset:34944
	ds_read_b64_tr_b16 v[64:65], v208 offset:37056
	ds_read_b64_tr_b16 v[236:237], v209
	ds_read_b64_tr_b16 v[238:239], v209 offset:1088
	ds_read_b64_tr_b16 v[240:241], v209 offset:128
	ds_read_b64_tr_b16 v[242:243], v209 offset:1216
	ds_read_b64_tr_b16 v[244:245], v209 offset:256
	ds_read_b64_tr_b16 v[246:247], v209 offset:1344
	ds_read_b64_tr_b16 v[122:123], v209 offset:384
	ds_read_b64_tr_b16 v[124:125], v209 offset:1472
	s_waitcnt lgkmcnt(6)
	v_mfma_f32_16x16x32_bf16 v[90:93], v[236:239], v[58:61], v[90:93]
	v_mfma_f32_16x16x32_bf16 v[94:97], v[236:239], v[62:65], v[94:97]
	ds_read_b64_tr_b16 v[236:237], v209 offset:512
	ds_read_b64_tr_b16 v[238:239], v209 offset:1600
	s_waitcnt lgkmcnt(6)
	v_mfma_f32_16x16x32_bf16 v[98:101], v[240:243], v[58:61], v[98:101]
	v_mfma_f32_16x16x32_bf16 v[102:105], v[240:243], v[62:65], v[102:105]
	ds_read_b64_tr_b16 v[240:241], v209 offset:640
	ds_read_b64_tr_b16 v[242:243], v209 offset:1728
	s_waitcnt lgkmcnt(6)
	v_mfma_f32_16x16x32_bf16 v[106:109], v[244:247], v[58:61], v[106:109]
	v_mfma_f32_16x16x32_bf16 v[110:113], v[244:247], v[62:65], v[110:113]
	ds_read_b64_tr_b16 v[244:245], v209 offset:768
	ds_read_b64_tr_b16 v[246:247], v209 offset:1856
	s_waitcnt lgkmcnt(6)
	v_mfma_f32_16x16x32_bf16 v[114:117], v[122:125], v[58:61], v[114:117]
	v_mfma_f32_16x16x32_bf16 v[118:121], v[122:125], v[62:65], v[118:121]
	ds_read_b64_tr_b16 v[122:123], v209 offset:896
	ds_read_b64_tr_b16 v[124:125], v209 offset:1984
	s_waitcnt lgkmcnt(6)
; #define LAS __attribute__((address_space(3)))
; __device__ __forceinline__ unsigned pk2(float lo, float hi) { const f32x2 v = {lo, hi}; return __builtin_bit_cast(unsigned, __builtin_convertvector(v, bf16x2_t)); }
; __device__ __forceinline__ s16x4 tr16(const LAS unsigned char* p) { return __builtin_bit_cast(s16x4, __builtin_amdgcn_ds_read_tr16_b64_v4i16((LAS s16x4*)p)); }
; __device__ __forceinline__ bf16x8 cat8(s16x4 lo, s16x4 hi) { return __builtin_shufflevector(lo, hi, 0, 1, 2, 3, 4, 5, 6, 7); }
; __device__ __forceinline__ f32x4 mfma16(bf16x8 a, bf16x8 b, f32x4 c) { return __builtin_amdgcn_mfma_f32_16x16x32_bf16(a, b, c, 0, 0, 0); }
; __device__ __forceinline__ void ret_scan(const bf16* proj, bf16* ST, bf16* FS, const float* dexp, LAS unsigned char* lds, int vb, int nb, int tid_in, int wave) {
;     ...
;             for (int ks = 0; ks < 4; ++ks) {
;                 const int rho = 8 * ks + 2 * g, lo8 = (qi >> 2) * 32 + (qi & 3) * 8;
;                 bf16x8 bfr[2];
; #pragma unroll
;                 for (int nt = 0; nt < 2; ++nt) { const LAS unsigned char* p = Vt + rho * 2112 + (2 * wave + nt) * 128 + lo8; bfr[nt] = cat8(tr16(p), tr16(p + 2112)); }
; #pragma unroll
;                 for (int m = 0; m < 8; ++m) { const LAS unsigned char* p = Kt + rho * 1088 + m * 128 + lo8; const bf16x8 af = cat8(tr16(p), tr16(p + 1088));
;                     acc[m][0] = mfma16(af, bfr[0], acc[m][0]); acc[m][1] = mfma16(af, bfr[1], acc[m][1]); }
;             }
;             dst_prev = step < 15 ? ST + ((size_t)(((base >> 7) + tgt) * 8 + h) * 2 + dir) * 65536 : FS + ((size_t)((vs - 8) * 8 + h) * 2 + dir) * 65536;
; #pragma unroll
;             for (int m = 0; m < 8; ++m)
; #pragma unroll
;                 for (int nt = 0; nt < 2; ++nt) { stq[m][nt].x = pk2(acc[m][nt].x, acc[m][nt].y); stq[m][nt].y = pk2(acc[m][nt].z, acc[m][nt].w); }
	v_mfma_f32_16x16x32_bf16 v[82:85], v[236:239], v[58:61], v[82:85]
	v_mfma_f32_16x16x32_bf16 v[86:89], v[236:239], v[62:65], v[86:89]
	s_waitcnt lgkmcnt(4)
	v_mfma_f32_16x16x32_bf16 v[74:77], v[240:243], v[58:61], v[74:77]
	v_mfma_f32_16x16x32_bf16 v[78:81], v[240:243], v[62:65], v[78:81]
	s_waitcnt lgkmcnt(2)
	v_mfma_f32_16x16x32_bf16 v[66:69], v[244:247], v[58:61], v[66:69]
	v_mfma_f32_16x16x32_bf16 v[70:73], v[244:247], v[62:65], v[70:73]
	s_waitcnt lgkmcnt(0)
	v_mfma_f32_16x16x32_bf16 v[54:57], v[122:125], v[58:61], v[54:57]
	v_mfma_f32_16x16x32_bf16 v[50:53], v[122:125], v[62:65], v[50:53]
	ds_read_b64_tr_b16 v[58:59], v208 offset:51712
	ds_read_b64_tr_b16 v[60:61], v208 offset:53824
	ds_read_b64_tr_b16 v[62:63], v208 offset:51840
	ds_read_b64_tr_b16 v[64:65], v208 offset:53952
	ds_read_b64_tr_b16 v[244:245], v209 offset:8704
	ds_read_b64_tr_b16 v[246:247], v209 offset:9792
	ds_read_b64_tr_b16 v[122:123], v209 offset:8832
	ds_read_b64_tr_b16 v[124:125], v209 offset:9920
	ds_read_b64_tr_b16 v[236:237], v209 offset:8960
	ds_read_b64_tr_b16 v[238:239], v209 offset:10048
	ds_read_b64_tr_b16 v[240:241], v209 offset:9088
	ds_read_b64_tr_b16 v[242:243], v209 offset:10176
	s_waitcnt lgkmcnt(6)
	v_mfma_f32_16x16x32_bf16 v[90:93], v[244:247], v[58:61], v[90:93]
	v_mfma_f32_16x16x32_bf16 v[94:97], v[244:247], v[62:65], v[94:97]
	ds_read_b64_tr_b16 v[244:245], v209 offset:9216
	ds_read_b64_tr_b16 v[246:247], v209 offset:10304
	s_waitcnt lgkmcnt(6)
	v_mfma_f32_16x16x32_bf16 v[98:101], v[122:125], v[58:61], v[98:101]
	v_mfma_f32_16x16x32_bf16 v[102:105], v[122:125], v[62:65], v[102:105]
	ds_read_b64_tr_b16 v[122:123], v209 offset:9344
	ds_read_b64_tr_b16 v[124:125], v209 offset:10432
	s_waitcnt lgkmcnt(6)
	v_mfma_f32_16x16x32_bf16 v[106:109], v[236:239], v[58:61], v[106:109]
	v_mfma_f32_16x16x32_bf16 v[110:113], v[236:239], v[62:65], v[110:113]
	s_waitcnt lgkmcnt(4)
	v_mfma_f32_16x16x32_bf16 v[114:117], v[240:243], v[58:61], v[114:117]
	v_mfma_f32_16x16x32_bf16 v[118:121], v[240:243], v[62:65], v[118:121]
	s_waitcnt lgkmcnt(2)
	v_mfma_f32_16x16x32_bf16 v[82:85], v[244:247], v[58:61], v[82:85]
	v_mfma_f32_16x16x32_bf16 v[86:89], v[244:247], v[62:65], v[86:89]
	s_waitcnt lgkmcnt(0)
	v_mfma_f32_16x16x32_bf16 v[126:129], v[122:125], v[58:61], v[74:77]
	s_nop 2
	ds_read_b64_tr_b16 v[74:75], v209 offset:9472
	ds_read_b64_tr_b16 v[76:77], v209 offset:10560
	s_waitcnt lgkmcnt(0)
	v_mfma_f32_16x16x32_bf16 v[130:133], v[74:77], v[58:61], v[66:69]
	s_nop 2
	ds_read_b64_tr_b16 v[66:67], v209 offset:9600
	ds_read_b64_tr_b16 v[68:69], v209 offset:10688
	v_mfma_f32_16x16x32_bf16 v[122:125], v[122:125], v[62:65], v[78:81]
	v_mfma_f32_16x16x32_bf16 v[134:137], v[74:77], v[62:65], v[70:73]
	s_waitcnt lgkmcnt(0)
	v_mfma_f32_16x16x32_bf16 v[138:141], v[66:69], v[58:61], v[54:57]
	ds_read_b64_tr_b16 v[168:169], v205 offset:51712
	ds_read_b64_tr_b16 v[170:171], v205 offset:53824
	ds_read_b64_tr_b16 v[226:227], v205 offset:51840
	ds_read_b64_tr_b16 v[228:229], v205 offset:53952
	ds_read_b64_tr_b16 v[54:55], v209 offset:17408
	ds_read_b64_tr_b16 v[56:57], v209 offset:18496
	v_mfma_f32_16x16x32_bf16 v[142:145], v[66:69], v[62:65], v[50:53]
	ds_read_b64_tr_b16 v[62:63], v209 offset:17536
	ds_read_b64_tr_b16 v[64:65], v209 offset:18624
	ds_read_b64_tr_b16 v[70:71], v209 offset:17664
	ds_read_b64_tr_b16 v[72:73], v209 offset:18752
	ds_read_b64_tr_b16 v[78:79], v209 offset:17792
	ds_read_b64_tr_b16 v[80:81], v209 offset:18880
	s_waitcnt lgkmcnt(6)
	v_mfma_f32_16x16x32_bf16 v[50:53], v[54:57], v[168:171], v[90:93]
	s_nop 2
	ds_read_b64_tr_b16 v[90:91], v209 offset:17920
	ds_read_b64_tr_b16 v[92:93], v209 offset:19008
	v_mfma_f32_16x16x32_bf16 v[54:57], v[54:57], v[226:229], v[94:97]
	s_nop 2
	ds_read_b64_tr_b16 v[94:95], v209 offset:18048
	ds_read_b64_tr_b16 v[96:97], v209 offset:19136
	s_waitcnt lgkmcnt(8)
	v_mfma_f32_16x16x32_bf16 v[58:61], v[62:65], v[168:171], v[98:101]
	v_mfma_f32_16x16x32_bf16 v[62:65], v[62:65], v[226:229], v[102:105]
	s_nop 2
	ds_read_b64_tr_b16 v[102:103], v209 offset:18176
	ds_read_b64_tr_b16 v[104:105], v209 offset:19264
	s_waitcnt lgkmcnt(8)
	v_mfma_f32_16x16x32_bf16 v[66:69], v[70:73], v[168:171], v[106:109]
	v_mfma_f32_16x16x32_bf16 v[70:73], v[70:73], v[226:229], v[110:113]
	s_nop 2
	ds_read_b64_tr_b16 v[110:111], v209 offset:18304
	ds_read_b64_tr_b16 v[112:113], v209 offset:19392
	s_waitcnt lgkmcnt(8)
	v_mfma_f32_16x16x32_bf16 v[74:77], v[78:81], v[168:171], v[114:117]
	v_mfma_f32_16x16x32_bf16 v[78:81], v[78:81], v[226:229], v[118:121]
	s_waitcnt lgkmcnt(6)
	v_mfma_f32_16x16x32_bf16 v[82:85], v[90:93], v[168:171], v[82:85]
	s_nop 0
	v_cvt_pk_bf16_f32 v118, v50, v51
	v_cvt_pk_bf16_f32 v119, v52, v53
	v_cvt_pk_bf16_f32 v120, v54, v55
	v_mfma_f32_16x16x32_bf16 v[86:89], v[90:93], v[226:229], v[86:89]
	v_cvt_pk_bf16_f32 v121, v56, v57
	s_waitcnt lgkmcnt(4)
	v_mfma_f32_16x16x32_bf16 v[90:93], v[94:97], v[168:171], v[126:129]
	v_mfma_f32_16x16x32_bf16 v[94:97], v[94:97], v[226:229], v[122:125]
	s_nop 1
	v_cvt_pk_bf16_f32 v126, v66, v67
	v_cvt_pk_bf16_f32 v127, v68, v69
	v_cvt_pk_bf16_f32 v128, v70, v71
	s_waitcnt lgkmcnt(2)
	v_mfma_f32_16x16x32_bf16 v[98:101], v[102:105], v[168:171], v[130:133]
	v_cvt_pk_bf16_f32 v122, v58, v59
	v_cvt_pk_bf16_f32 v123, v60, v61
	v_cvt_pk_bf16_f32 v124, v62, v63
	v_mfma_f32_16x16x32_bf16 v[102:105], v[102:105], v[226:229], v[134:137]
	v_cvt_pk_bf16_f32 v125, v64, v65
	v_cvt_pk_bf16_f32 v129, v72, v73
	v_cvt_pk_bf16_f32 v130, v74, v75
	s_waitcnt lgkmcnt(0)
	v_mfma_f32_16x16x32_bf16 v[106:109], v[110:113], v[168:171], v[138:141]
	v_cvt_pk_bf16_f32 v131, v76, v77
	v_cvt_pk_bf16_f32 v132, v78, v79
	v_cvt_pk_bf16_f32 v133, v80, v81
	v_mfma_f32_16x16x32_bf16 v[110:113], v[110:113], v[226:229], v[142:145]
	v_cvt_pk_bf16_f32 v134, v82, v83
	v_cvt_pk_bf16_f32 v135, v84, v85
	v_cvt_pk_bf16_f32 v136, v86, v87
	v_cvt_pk_bf16_f32 v137, v88, v89
	v_cvt_pk_bf16_f32 v138, v90, v91
	v_cvt_pk_bf16_f32 v139, v92, v93
	v_cvt_pk_bf16_f32 v140, v94, v95
	v_cvt_pk_bf16_f32 v141, v96, v97
	v_cvt_pk_bf16_f32 v142, v98, v99
	v_cvt_pk_bf16_f32 v143, v100, v101
	v_cvt_pk_bf16_f32 v144, v102, v103
	v_cvt_pk_bf16_f32 v145, v104, v105
	v_cvt_pk_bf16_f32 v168, v106, v107
	v_cvt_pk_bf16_f32 v169, v108, v109
	v_cvt_pk_bf16_f32 v170, v110, v111
	v_cvt_pk_bf16_f32 v171, v112, v113
